# layer-0 out-proj GEMM epilogue (f32 residual source): the 32 serialized x loads per tile replaced by a 3-row rolling window of batched loads
# speedup vs baseline: 1.0109x; 1.0109x over previous
.LBB0_797:
	v_lshl_add_u64 v[152:153], v[146:147], 2, v[150:151]
	v_lshlrev_b64 v[162:163], 12, v[148:149]
	s_mov_b64 s[4:5], s[6:7]
	v_lshl_add_u64 v[150:151], s[4:5], 0, v[162:163]
	v_lshl_add_u64 v[150:151], v[146:147], 1, v[150:151]
	s_mov_b64 s[6:7], 0x20000
	s_mov_b64 s[28:29], 0x10000
	global_load_dwordx4 v[166:169], v[152:153], off
	global_load_dwordx4 v[170:173], v[152:153], off offset:16
	global_load_dwordx4 v[174:177], v[152:153], off offset:512
	global_load_dwordx4 v[178:181], v[152:153], off offset:528
	v_lshl_add_u64 v[152:153], v[152:153], 0, s[6:7]
	global_load_dwordx4 v[182:185], v[152:153], off
	global_load_dwordx4 v[196:199], v[152:153], off offset:16
	global_load_dwordx4 v[200:203], v[152:153], off offset:512
	global_load_dwordx4 v[226:229], v[152:153], off offset:528
	v_lshl_add_u64 v[152:153], v[152:153], 0, s[6:7]
	global_load_dwordx4 v[230:233], v[152:153], off
	global_load_dwordx4 v[234:237], v[152:153], off offset:16
	global_load_dwordx4 v[238:241], v[152:153], off offset:512
	global_load_dwordx4 v[242:245], v[152:153], off offset:528
	v_lshl_add_u64 v[152:153], v[152:153], 0, s[6:7]
	s_waitcnt vmcnt(10)
	v_pk_fma_f32 v[154:155], v[126:127], v[142:143], v[166:167]
	v_pk_fma_f32 v[156:157], v[128:129], v[144:145], v[168:169]
	v_pk_fma_f32 v[158:159], v[122:123], v[138:139], v[170:171]
	v_pk_fma_f32 v[160:161], v[124:125], v[140:141], v[172:173]
	v_cvt_pk_bf16_f32 v162, v154, v155
	v_cvt_pk_bf16_f32 v163, v156, v157
	v_cvt_pk_bf16_f32 v164, v158, v159
	v_cvt_pk_bf16_f32 v165, v160, v161
	global_store_dwordx4 v[150:151], v[162:165], off
	s_waitcnt vmcnt(9)
	v_pk_fma_f32 v[154:155], v[118:119], v[134:135], v[174:175]
	v_pk_fma_f32 v[156:157], v[120:121], v[136:137], v[176:177]
	v_pk_fma_f32 v[158:159], v[110:111], v[130:131], v[178:179]
	v_pk_fma_f32 v[160:161], v[112:113], v[132:133], v[180:181]
	v_cvt_pk_bf16_f32 v162, v154, v155
	v_cvt_pk_bf16_f32 v163, v156, v157
	v_cvt_pk_bf16_f32 v164, v158, v159
	v_cvt_pk_bf16_f32 v165, v160, v161
	global_store_dwordx4 v[150:151], v[162:165], off offset:256
	v_lshl_add_u64 v[150:151], v[150:151], 0, s[28:29]
	global_load_dwordx4 v[166:169], v[152:153], off
	global_load_dwordx4 v[170:173], v[152:153], off offset:16
	global_load_dwordx4 v[174:177], v[152:153], off offset:512
	global_load_dwordx4 v[178:181], v[152:153], off offset:528
	v_add_co_u32_e32 v152, vcc, 0xa0000, v152
	s_nop 1
	v_addc_co_u32_e32 v153, vcc, 0, v153, vcc
	s_waitcnt vmcnt(12)
	v_pk_fma_f32 v[154:155], v[114:115], v[142:143], v[182:183]
	v_pk_fma_f32 v[156:157], v[116:117], v[144:145], v[184:185]
	v_pk_fma_f32 v[158:159], v[106:107], v[138:139], v[196:197]
	v_pk_fma_f32 v[160:161], v[108:109], v[140:141], v[198:199]
	v_cvt_pk_bf16_f32 v162, v154, v155
	v_cvt_pk_bf16_f32 v163, v156, v157
	v_cvt_pk_bf16_f32 v164, v158, v159
	v_cvt_pk_bf16_f32 v165, v160, v161
	global_store_dwordx4 v[150:151], v[162:165], off
	s_waitcnt vmcnt(11)
	v_pk_fma_f32 v[154:155], v[102:103], v[134:135], v[200:201]
	v_pk_fma_f32 v[156:157], v[104:105], v[136:137], v[202:203]
	v_pk_fma_f32 v[158:159], v[94:95], v[130:131], v[226:227]
	v_pk_fma_f32 v[160:161], v[96:97], v[132:133], v[228:229]
	v_cvt_pk_bf16_f32 v162, v154, v155
	v_cvt_pk_bf16_f32 v163, v156, v157
	v_cvt_pk_bf16_f32 v164, v158, v159
	v_cvt_pk_bf16_f32 v165, v160, v161
	global_store_dwordx4 v[150:151], v[162:165], off offset:256
	v_lshl_add_u64 v[150:151], v[150:151], 0, s[28:29]
	global_load_dwordx4 v[182:185], v[152:153], off
	global_load_dwordx4 v[196:199], v[152:153], off offset:16
	global_load_dwordx4 v[200:203], v[152:153], off offset:512
	global_load_dwordx4 v[226:229], v[152:153], off offset:528
	v_lshl_add_u64 v[152:153], v[152:153], 0, s[6:7]
	s_waitcnt vmcnt(14)
	v_pk_fma_f32 v[154:155], v[98:99], v[142:143], v[230:231]
	v_pk_fma_f32 v[156:157], v[100:101], v[144:145], v[232:233]
	v_pk_fma_f32 v[158:159], v[90:91], v[138:139], v[234:235]
	v_pk_fma_f32 v[160:161], v[92:93], v[140:141], v[236:237]
	v_cvt_pk_bf16_f32 v162, v154, v155
	v_cvt_pk_bf16_f32 v163, v156, v157
	v_cvt_pk_bf16_f32 v164, v158, v159
	v_cvt_pk_bf16_f32 v165, v160, v161
	global_store_dwordx4 v[150:151], v[162:165], off
	s_waitcnt vmcnt(13)
	v_pk_fma_f32 v[154:155], v[86:87], v[134:135], v[238:239]
	v_pk_fma_f32 v[156:157], v[88:89], v[136:137], v[240:241]
	v_pk_fma_f32 v[158:159], v[78:79], v[130:131], v[242:243]
	v_pk_fma_f32 v[160:161], v[80:81], v[132:133], v[244:245]
	v_cvt_pk_bf16_f32 v162, v154, v155
	v_cvt_pk_bf16_f32 v163, v156, v157
	v_cvt_pk_bf16_f32 v164, v158, v159
	v_cvt_pk_bf16_f32 v165, v160, v161
	global_store_dwordx4 v[150:151], v[162:165], off offset:256
	v_lshl_add_u64 v[150:151], v[150:151], 0, s[28:29]
	global_load_dwordx4 v[230:233], v[152:153], off
	global_load_dwordx4 v[234:237], v[152:153], off offset:16
	global_load_dwordx4 v[238:241], v[152:153], off offset:512
	global_load_dwordx4 v[242:245], v[152:153], off offset:528
	v_lshl_add_u64 v[152:153], v[152:153], 0, s[6:7]
	s_waitcnt vmcnt(14)
	v_pk_fma_f32 v[154:155], v[82:83], v[142:143], v[166:167]
	v_pk_fma_f32 v[156:157], v[84:85], v[144:145], v[168:169]
	v_pk_fma_f32 v[158:159], v[74:75], v[138:139], v[170:171]
	v_pk_fma_f32 v[160:161], v[76:77], v[140:141], v[172:173]
	v_cvt_pk_bf16_f32 v162, v154, v155
	v_cvt_pk_bf16_f32 v163, v156, v157
	v_cvt_pk_bf16_f32 v164, v158, v159
	v_cvt_pk_bf16_f32 v165, v160, v161
	global_store_dwordx4 v[150:151], v[162:165], off
	s_waitcnt vmcnt(13)
	v_pk_fma_f32 v[154:155], v[70:71], v[134:135], v[174:175]
	v_pk_fma_f32 v[156:157], v[72:73], v[136:137], v[176:177]
	v_pk_fma_f32 v[158:159], v[66:67], v[130:131], v[178:179]
	v_pk_fma_f32 v[160:161], v[68:69], v[132:133], v[180:181]
	v_cvt_pk_bf16_f32 v162, v154, v155
	v_cvt_pk_bf16_f32 v163, v156, v157
	v_cvt_pk_bf16_f32 v164, v158, v159
	v_cvt_pk_bf16_f32 v165, v160, v161
	global_store_dwordx4 v[150:151], v[162:165], off offset:256
	v_add_co_u32_e32 v150, vcc, 0x50000, v150
	s_nop 1
	v_addc_co_u32_e32 v151, vcc, 0, v151, vcc
	global_load_dwordx4 v[166:169], v[152:153], off
	global_load_dwordx4 v[170:173], v[152:153], off offset:16
	global_load_dwordx4 v[174:177], v[152:153], off offset:512
	global_load_dwordx4 v[178:181], v[152:153], off offset:528
	v_lshl_add_u64 v[152:153], v[152:153], 0, s[6:7]
	s_waitcnt vmcnt(14)
	v_pk_fma_f32 v[154:155], v[62:63], v[142:143], v[182:183]
	v_pk_fma_f32 v[156:157], v[64:65], v[144:145], v[184:185]
	v_pk_fma_f32 v[158:159], v[58:59], v[138:139], v[196:197]
	v_pk_fma_f32 v[160:161], v[60:61], v[140:141], v[198:199]
	v_cvt_pk_bf16_f32 v162, v154, v155
	v_cvt_pk_bf16_f32 v163, v156, v157
	v_cvt_pk_bf16_f32 v164, v158, v159
	v_cvt_pk_bf16_f32 v165, v160, v161
	global_store_dwordx4 v[150:151], v[162:165], off
	s_waitcnt vmcnt(13)
	v_pk_fma_f32 v[154:155], v[54:55], v[134:135], v[200:201]
	v_pk_fma_f32 v[156:157], v[56:57], v[136:137], v[202:203]
	v_pk_fma_f32 v[158:159], v[46:47], v[130:131], v[226:227]
	v_pk_fma_f32 v[160:161], v[48:49], v[132:133], v[228:229]
	v_cvt_pk_bf16_f32 v162, v154, v155
	v_cvt_pk_bf16_f32 v163, v156, v157
	v_cvt_pk_bf16_f32 v164, v158, v159
	v_cvt_pk_bf16_f32 v165, v160, v161
	global_store_dwordx4 v[150:151], v[162:165], off offset:256
	v_lshl_add_u64 v[150:151], v[150:151], 0, s[28:29]
	global_load_dwordx4 v[182:185], v[152:153], off
	global_load_dwordx4 v[196:199], v[152:153], off offset:16
	global_load_dwordx4 v[200:203], v[152:153], off offset:512
	global_load_dwordx4 v[226:229], v[152:153], off offset:528
	s_waitcnt vmcnt(14)
	v_pk_fma_f32 v[154:155], v[50:51], v[142:143], v[230:231]
	v_pk_fma_f32 v[156:157], v[52:53], v[144:145], v[232:233]
	v_pk_fma_f32 v[158:159], v[42:43], v[138:139], v[234:235]
	v_pk_fma_f32 v[160:161], v[44:45], v[140:141], v[236:237]
	v_cvt_pk_bf16_f32 v162, v154, v155
	v_cvt_pk_bf16_f32 v163, v156, v157
	v_cvt_pk_bf16_f32 v164, v158, v159
	v_cvt_pk_bf16_f32 v165, v160, v161
	global_store_dwordx4 v[150:151], v[162:165], off
	s_waitcnt vmcnt(13)
	v_pk_fma_f32 v[154:155], v[38:39], v[134:135], v[238:239]
	v_pk_fma_f32 v[156:157], v[40:41], v[136:137], v[240:241]
	v_pk_fma_f32 v[158:159], v[30:31], v[130:131], v[242:243]
	v_pk_fma_f32 v[160:161], v[32:33], v[132:133], v[244:245]
	v_cvt_pk_bf16_f32 v162, v154, v155
	v_cvt_pk_bf16_f32 v163, v156, v157
	v_cvt_pk_bf16_f32 v164, v158, v159
	v_cvt_pk_bf16_f32 v165, v160, v161
	global_store_dwordx4 v[150:151], v[162:165], off offset:256
	v_lshl_add_u64 v[150:151], v[150:151], 0, s[28:29]
	s_waitcnt vmcnt(10)
	v_pk_fma_f32 v[154:155], v[34:35], v[142:143], v[166:167]
	v_pk_fma_f32 v[156:157], v[36:37], v[144:145], v[168:169]
	v_pk_fma_f32 v[158:159], v[26:27], v[138:139], v[170:171]
	v_pk_fma_f32 v[160:161], v[28:29], v[140:141], v[172:173]
	v_cvt_pk_bf16_f32 v162, v154, v155
	v_cvt_pk_bf16_f32 v163, v156, v157
	v_cvt_pk_bf16_f32 v164, v158, v159
	v_cvt_pk_bf16_f32 v165, v160, v161
	global_store_dwordx4 v[150:151], v[162:165], off
	s_waitcnt vmcnt(9)
	v_pk_fma_f32 v[154:155], v[22:23], v[134:135], v[174:175]
	v_pk_fma_f32 v[156:157], v[24:25], v[136:137], v[176:177]
	v_pk_fma_f32 v[158:159], v[12:13], v[130:131], v[178:179]
	v_pk_fma_f32 v[160:161], v[14:15], v[132:133], v[180:181]
	v_cvt_pk_bf16_f32 v162, v154, v155
	v_cvt_pk_bf16_f32 v163, v156, v157
	v_cvt_pk_bf16_f32 v164, v158, v159
	v_cvt_pk_bf16_f32 v165, v160, v161
	global_store_dwordx4 v[150:151], v[162:165], off offset:256
	v_lshl_add_u64 v[150:151], v[150:151], 0, s[28:29]
	s_waitcnt vmcnt(6)
	v_pk_fma_f32 v[154:155], v[18:19], v[142:143], v[182:183]
	v_pk_fma_f32 v[156:157], v[20:21], v[144:145], v[184:185]
	v_pk_fma_f32 v[158:159], v[8:9], v[138:139], v[196:197]
	v_pk_fma_f32 v[160:161], v[10:11], v[140:141], v[198:199]
	v_cvt_pk_bf16_f32 v162, v154, v155
	v_cvt_pk_bf16_f32 v163, v156, v157
	v_cvt_pk_bf16_f32 v164, v158, v159
	v_cvt_pk_bf16_f32 v165, v160, v161
	global_store_dwordx4 v[150:151], v[162:165], off
	s_waitcnt vmcnt(5)
	v_pk_fma_f32 v[154:155], v[4:5], v[134:135], v[200:201]
	v_pk_fma_f32 v[156:157], v[6:7], v[136:137], v[202:203]
	v_pk_fma_f32 v[158:159], v[0:1], v[130:131], v[226:227]
	v_pk_fma_f32 v[160:161], v[2:3], v[132:133], v[228:229]
	v_cvt_pk_bf16_f32 v162, v154, v155
	v_cvt_pk_bf16_f32 v163, v156, v157
	v_cvt_pk_bf16_f32 v164, v158, v159
	v_cvt_pk_bf16_f32 v165, v160, v161
	global_store_dwordx4 v[150:151], v[162:165], off offset:256
	s_mov_b64 s[6:7], s[8:9]
	s_branch .LBB0_799
